# SwiGLU activation stores without the nt cache hint (the w2 GEMM re-reads them)
# speedup vs baseline: 1.0133x; 1.0133x over previous
.LBB0_401:
	ds_read2_b32 v[156:157], v153 offset1:16
	s_waitcnt lgkmcnt(0)
	v_add_u32_e32 v128, 0x1000, v153
	ds_read2_b32 v[158:159], v128 offset1:16
	ds_read2_b32 v[148:149], v153 offset0:32 offset1:48
	ds_read2_b32 v[146:147], v128 offset0:32 offset1:48
	ds_read2_b32 v[144:145], v153 offset0:64 offset1:80
	ds_read2_b32 v[142:143], v128 offset0:64 offset1:80
	ds_read2_b32 v[130:131], v153 offset0:96 offset1:112
	ds_read2_b32 v[128:129], v128 offset0:96 offset1:112
	v_pk_mul_f32 v[114:115], v[114:115], v[118:119]
	v_pk_mul_f32 v[112:113], v[112:113], v[116:117]
	v_pk_mul_f32 v[160:161], v[120:121], v[156:157] op_sel_hi:[1,0]
	v_pk_mul_f32 v[162:163], v[122:123], v[156:157] op_sel_hi:[1,0]
	v_exp_f32_e32 v161, v161
	v_pk_mul_f32 v[122:123], v[126:127], v[122:123]
	v_exp_f32_e32 v126, v163
	v_pk_mul_f32 v[120:121], v[124:125], v[120:121]
	s_waitcnt lgkmcnt(0)
	v_fma_f32 v161, v161, v158, v158
	v_rcp_f32_e32 v165, v161
	v_exp_f32_e32 v161, v162
	v_fma_f32 v125, v126, v158, v158
	v_rcp_f32_e32 v125, v125
	v_pk_mul_f32 v[126:127], v[116:117], v[156:157] op_sel_hi:[1,0]
	v_fma_f32 v124, v161, v158, v158
	v_rcp_f32_e32 v124, v124
	v_exp_f32_e32 v164, v160
	v_exp_f32_e32 v126, v126
	v_exp_f32_e32 v127, v127
	v_pk_mul_f32 v[122:123], v[122:123], v[124:125]
	v_pk_mul_f32 v[124:125], v[118:119], v[156:157] op_sel_hi:[1,0]
	v_fma_f32 v164, v164, v158, v158
	v_exp_f32_e32 v124, v124
	v_exp_f32_e32 v125, v125
	v_fma_f32 v126, v126, v158, v158
	v_fma_f32 v127, v127, v158, v158
	v_fma_f32 v124, v124, v158, v158
	v_fma_f32 v125, v125, v158, v158
	v_rcp_f32_e32 v124, v124
	v_rcp_f32_e32 v125, v125
	v_rcp_f32_e32 v164, v164
	v_rcp_f32_e32 v126, v126
	v_rcp_f32_e32 v127, v127
	v_pk_mul_f32 v[118:119], v[114:115], v[124:125]
	v_or_b32_e32 v166, s10, v150
	v_lshl_or_b32 v160, s67, 8, v154
	v_pk_mul_f32 v[120:121], v[120:121], v[164:165]
	v_pk_mul_f32 v[112:113], v[112:113], v[126:127]
	v_cvt_pk_bf16_f32 v117, v118, v119
	s_movk_i32 s4, 0x1600
	v_mov_b32_e32 v118, v157
	v_cvt_pk_bf16_f32 v114, v120, v121
	v_cvt_pk_bf16_f32 v116, v112, v113
	v_mad_u64_u32 v[112:113], s[4:5], v166, s4, v[160:161]
	v_pk_mul_f32 v[120:121], v[108:109], v[118:119] op_sel_hi:[1,0]
	v_cvt_pk_bf16_f32 v115, v122, v123
	v_exp_f32_e32 v113, v120
	global_store_dwordx4 v112, v[114:117], s[18:19]
	v_pk_mul_f32 v[106:107], v[106:107], v[110:111]
	v_pk_mul_f32 v[104:105], v[104:105], v[108:109]
	v_exp_f32_e32 v117, v121
	v_fma_f32 v113, v113, v159, v159
	v_pk_mul_f32 v[114:115], v[110:111], v[118:119] op_sel_hi:[1,0]
	v_rcp_f32_e32 v116, v113
	v_fma_f32 v113, v117, v159, v159
	v_rcp_f32_e32 v117, v113
	v_exp_f32_e32 v113, v114
	v_exp_f32_e32 v110, v115
	v_pk_mul_f32 v[98:99], v[98:99], v[102:103]
	v_pk_mul_f32 v[96:97], v[96:97], v[100:101]
	v_fma_f32 v108, v113, v159, v159
	v_fma_f32 v109, v110, v159, v159
	v_rcp_f32_e32 v108, v108
	v_rcp_f32_e32 v109, v109
	v_pk_mul_f32 v[110:111], v[100:101], v[118:119] op_sel_hi:[1,0]
	v_pk_mul_f32 v[104:105], v[104:105], v[116:117]
	v_exp_f32_e32 v110, v110
	v_pk_mul_f32 v[106:107], v[106:107], v[108:109]
	v_pk_mul_f32 v[108:109], v[102:103], v[118:119] op_sel_hi:[1,0]
	v_exp_f32_e32 v111, v111
	v_exp_f32_e32 v108, v108
	v_exp_f32_e32 v109, v109
	v_fma_f32 v110, v110, v159, v159
	v_fma_f32 v111, v111, v159, v159
	v_fma_f32 v108, v108, v159, v159
	v_fmac_f32_e32 v159, v109, v159
	v_rcp_f32_e32 v110, v110
	v_rcp_f32_e32 v111, v111
	v_rcp_f32_e32 v108, v108
	v_rcp_f32_e32 v109, v159
	v_pk_mul_f32 v[90:91], v[90:91], v[94:95]
	v_pk_mul_f32 v[100:101], v[96:97], v[110:111]
	v_cvt_pk_bf16_f32 v96, v104, v105
	v_pk_mul_f32 v[102:103], v[98:99], v[108:109]
	v_cvt_pk_bf16_f32 v97, v106, v107
	v_cvt_pk_bf16_f32 v98, v100, v101
	v_cvt_pk_bf16_f32 v99, v102, v103
	v_add_u32_e32 v102, 0x16000, v112
	global_store_dwordx4 v102, v[96:99], s[18:19]
	v_pk_mul_f32 v[100:101], v[92:93], v[148:149] op_sel_hi:[1,0]
	v_pk_mul_f32 v[88:89], v[88:89], v[92:93]
	v_pk_mul_f32 v[96:97], v[94:95], v[148:149] op_sel_hi:[1,0]
	v_exp_f32_e32 v100, v100
	v_exp_f32_e32 v96, v96
	v_exp_f32_e32 v94, v97
	v_exp_f32_e32 v99, v101
	v_fma_f32 v98, v100, v146, v146
	v_fma_f32 v92, v96, v146, v146
	v_fma_f32 v93, v94, v146, v146
	v_rcp_f32_e32 v92, v92
	v_rcp_f32_e32 v93, v93
	v_pk_mul_f32 v[94:95], v[84:85], v[148:149] op_sel_hi:[1,0]
	v_fma_f32 v99, v99, v146, v146
	v_exp_f32_e32 v94, v94
	v_pk_mul_f32 v[90:91], v[90:91], v[92:93]
	v_pk_mul_f32 v[92:93], v[86:87], v[148:149] op_sel_hi:[1,0]
	v_exp_f32_e32 v95, v95
	v_exp_f32_e32 v92, v92
	v_exp_f32_e32 v93, v93
	v_fma_f32 v94, v94, v146, v146
	v_fma_f32 v95, v95, v146, v146
	v_fma_f32 v92, v92, v146, v146
	v_fma_f32 v93, v93, v146, v146
	v_rcp_f32_e32 v98, v98
	v_rcp_f32_e32 v99, v99
	v_rcp_f32_e32 v94, v94
	v_rcp_f32_e32 v95, v95
	v_rcp_f32_e32 v92, v92
	v_rcp_f32_e32 v93, v93
	v_pk_mul_f32 v[82:83], v[82:83], v[86:87]
	v_pk_mul_f32 v[80:81], v[80:81], v[84:85]
	v_pk_mul_f32 v[88:89], v[88:89], v[98:99]
	v_pk_mul_f32 v[84:85], v[80:81], v[94:95]
	v_pk_mul_f32 v[86:87], v[82:83], v[92:93]
	v_cvt_pk_bf16_f32 v80, v88, v89
	v_cvt_pk_bf16_f32 v81, v90, v91
	v_cvt_pk_bf16_f32 v82, v84, v85
	v_cvt_pk_bf16_f32 v83, v86, v87
	v_add_u32_e32 v85, 0x2c000, v112
	v_mov_b32_e32 v84, v149
	global_store_dwordx4 v85, v[80:83], s[18:19]
	v_pk_mul_f32 v[74:75], v[74:75], v[78:79]
	v_pk_mul_f32 v[86:87], v[76:77], v[84:85] op_sel_hi:[1,0]
	v_pk_mul_f32 v[80:81], v[78:79], v[84:85] op_sel_hi:[1,0]
	v_pk_mul_f32 v[72:73], v[72:73], v[76:77]
	v_exp_f32_e32 v80, v80
	v_exp_f32_e32 v78, v81
	v_exp_f32_e32 v86, v86
	v_exp_f32_e32 v83, v87
	v_fma_f32 v76, v80, v147, v147
	v_fma_f32 v77, v78, v147, v147
	v_rcp_f32_e32 v76, v76
	v_rcp_f32_e32 v77, v77
	v_pk_mul_f32 v[78:79], v[68:69], v[84:85] op_sel_hi:[1,0]
	v_fma_f32 v82, v86, v147, v147
	v_exp_f32_e32 v78, v78
	v_pk_mul_f32 v[74:75], v[74:75], v[76:77]
	v_pk_mul_f32 v[76:77], v[70:71], v[84:85] op_sel_hi:[1,0]
	v_exp_f32_e32 v79, v79
	v_exp_f32_e32 v76, v76
	v_exp_f32_e32 v77, v77
	v_fma_f32 v83, v83, v147, v147
	v_fma_f32 v78, v78, v147, v147
	v_fma_f32 v79, v79, v147, v147
	v_fma_f32 v76, v76, v147, v147
	v_fmac_f32_e32 v147, v77, v147
	v_rcp_f32_e32 v82, v82
	v_rcp_f32_e32 v83, v83
	v_rcp_f32_e32 v78, v78
	v_rcp_f32_e32 v79, v79
	v_rcp_f32_e32 v76, v76
	v_rcp_f32_e32 v77, v147
	v_pk_mul_f32 v[66:67], v[66:67], v[70:71]
	v_pk_mul_f32 v[64:65], v[64:65], v[68:69]
	v_pk_mul_f32 v[72:73], v[72:73], v[82:83]
	v_pk_mul_f32 v[68:69], v[64:65], v[78:79]
	v_pk_mul_f32 v[70:71], v[66:67], v[76:77]
	v_cvt_pk_bf16_f32 v64, v72, v73
	v_cvt_pk_bf16_f32 v65, v74, v75
	v_cvt_pk_bf16_f32 v66, v68, v69
	v_cvt_pk_bf16_f32 v67, v70, v71
	v_add_u32_e32 v70, 0x42000, v112
	global_store_dwordx4 v70, v[64:67], s[18:19]
	v_pk_mul_f32 v[58:59], v[58:59], v[62:63]
	v_pk_mul_f32 v[68:69], v[60:61], v[144:145] op_sel_hi:[1,0]
	v_pk_mul_f32 v[64:65], v[62:63], v[144:145] op_sel_hi:[1,0]
	v_pk_mul_f32 v[56:57], v[56:57], v[60:61]
	v_exp_f32_e32 v64, v64
	v_exp_f32_e32 v62, v65
	v_exp_f32_e32 v68, v68
	v_exp_f32_e32 v67, v69
	v_fma_f32 v60, v64, v142, v142
	v_fma_f32 v61, v62, v142, v142
	v_rcp_f32_e32 v60, v60
	v_rcp_f32_e32 v61, v61
	v_pk_mul_f32 v[62:63], v[52:53], v[144:145] op_sel_hi:[1,0]
	v_fma_f32 v66, v68, v142, v142
	v_exp_f32_e32 v62, v62
	v_pk_mul_f32 v[58:59], v[58:59], v[60:61]
	v_pk_mul_f32 v[60:61], v[54:55], v[144:145] op_sel_hi:[1,0]
	v_exp_f32_e32 v63, v63
	v_exp_f32_e32 v60, v60
	v_exp_f32_e32 v61, v61
	v_fma_f32 v67, v67, v142, v142
	v_fma_f32 v62, v62, v142, v142
	v_fma_f32 v63, v63, v142, v142
	v_fma_f32 v60, v60, v142, v142
	v_fma_f32 v61, v61, v142, v142
	v_rcp_f32_e32 v66, v66
	v_rcp_f32_e32 v67, v67
	v_rcp_f32_e32 v62, v62
	v_rcp_f32_e32 v63, v63
	v_rcp_f32_e32 v60, v60
	v_rcp_f32_e32 v61, v61
	v_pk_mul_f32 v[50:51], v[50:51], v[54:55]
	v_pk_mul_f32 v[48:49], v[48:49], v[52:53]
	v_pk_mul_f32 v[56:57], v[56:57], v[66:67]
	v_pk_mul_f32 v[52:53], v[48:49], v[62:63]
	v_pk_mul_f32 v[54:55], v[50:51], v[60:61]
	v_cvt_pk_bf16_f32 v48, v56, v57
	v_cvt_pk_bf16_f32 v49, v58, v59
	v_cvt_pk_bf16_f32 v50, v52, v53
	v_cvt_pk_bf16_f32 v51, v54, v55
	v_add_u32_e32 v53, 0xb0000, v112
	v_mov_b32_e32 v52, v145
	global_store_dwordx4 v53, v[48:51], s[18:19]
	v_pk_mul_f32 v[42:43], v[42:43], v[46:47]
	v_pk_mul_f32 v[54:55], v[44:45], v[52:53] op_sel_hi:[1,0]
	v_pk_mul_f32 v[48:49], v[46:47], v[52:53] op_sel_hi:[1,0]
	v_pk_mul_f32 v[40:41], v[40:41], v[44:45]
	v_exp_f32_e32 v48, v48
	v_exp_f32_e32 v46, v49
	v_exp_f32_e32 v54, v54
	v_exp_f32_e32 v51, v55
	v_fma_f32 v44, v48, v143, v143
	v_fma_f32 v45, v46, v143, v143
	v_rcp_f32_e32 v44, v44
	v_rcp_f32_e32 v45, v45
	v_pk_mul_f32 v[46:47], v[36:37], v[52:53] op_sel_hi:[1,0]
	v_fma_f32 v50, v54, v143, v143
	v_exp_f32_e32 v46, v46
	v_pk_mul_f32 v[42:43], v[42:43], v[44:45]
	v_pk_mul_f32 v[44:45], v[38:39], v[52:53] op_sel_hi:[1,0]
	v_exp_f32_e32 v47, v47
	v_exp_f32_e32 v44, v44
	v_exp_f32_e32 v45, v45
	v_fma_f32 v51, v51, v143, v143
	v_fma_f32 v46, v46, v143, v143
	v_fma_f32 v47, v47, v143, v143
	v_fma_f32 v44, v44, v143, v143
	v_fmac_f32_e32 v143, v45, v143
	v_rcp_f32_e32 v50, v50
	v_rcp_f32_e32 v51, v51
	v_rcp_f32_e32 v46, v46
	v_rcp_f32_e32 v47, v47
	v_rcp_f32_e32 v44, v44
	v_rcp_f32_e32 v45, v143
	v_pk_mul_f32 v[34:35], v[34:35], v[38:39]
	v_pk_mul_f32 v[32:33], v[32:33], v[36:37]
	v_pk_mul_f32 v[40:41], v[40:41], v[50:51]
	v_pk_mul_f32 v[36:37], v[32:33], v[46:47]
	v_pk_mul_f32 v[38:39], v[34:35], v[44:45]
	v_cvt_pk_bf16_f32 v32, v40, v41
	v_cvt_pk_bf16_f32 v33, v42, v43
	v_cvt_pk_bf16_f32 v34, v36, v37
	v_cvt_pk_bf16_f32 v35, v38, v39
	v_add_u32_e32 v38, 0xc6000, v112
	global_store_dwordx4 v38, v[32:35], s[18:19]
	v_pk_mul_f32 v[26:27], v[26:27], v[30:31]
	v_pk_mul_f32 v[36:37], v[28:29], v[130:131] op_sel_hi:[1,0]
	v_pk_mul_f32 v[32:33], v[30:31], v[130:131] op_sel_hi:[1,0]
	v_pk_mul_f32 v[24:25], v[24:25], v[28:29]
	v_exp_f32_e32 v32, v32
	v_exp_f32_e32 v30, v33
	v_exp_f32_e32 v36, v36
	v_exp_f32_e32 v35, v37
	v_fma_f32 v28, v32, v128, v128
	v_fma_f32 v29, v30, v128, v128
	v_rcp_f32_e32 v28, v28
	v_rcp_f32_e32 v29, v29
	v_pk_mul_f32 v[30:31], v[20:21], v[130:131] op_sel_hi:[1,0]
	v_fma_f32 v34, v36, v128, v128
	v_exp_f32_e32 v30, v30
	v_pk_mul_f32 v[26:27], v[26:27], v[28:29]
	v_pk_mul_f32 v[28:29], v[22:23], v[130:131] op_sel_hi:[1,0]
	v_exp_f32_e32 v31, v31
	v_exp_f32_e32 v28, v28
	v_exp_f32_e32 v29, v29
	v_fma_f32 v35, v35, v128, v128
	v_fma_f32 v30, v30, v128, v128
	v_fma_f32 v31, v31, v128, v128
	v_fma_f32 v28, v28, v128, v128
	v_fma_f32 v29, v29, v128, v128
	v_rcp_f32_e32 v34, v34
	v_rcp_f32_e32 v35, v35
	v_rcp_f32_e32 v30, v30
	v_rcp_f32_e32 v31, v31
	v_rcp_f32_e32 v28, v28
	v_rcp_f32_e32 v29, v29
	v_pk_mul_f32 v[18:19], v[18:19], v[22:23]
	v_pk_mul_f32 v[16:17], v[16:17], v[20:21]
	v_pk_mul_f32 v[24:25], v[24:25], v[34:35]
	v_pk_mul_f32 v[20:21], v[16:17], v[30:31]
	v_pk_mul_f32 v[22:23], v[18:19], v[28:29]
	v_cvt_pk_bf16_f32 v16, v24, v25
	v_cvt_pk_bf16_f32 v17, v26, v27
	v_cvt_pk_bf16_f32 v18, v20, v21
	v_cvt_pk_bf16_f32 v19, v22, v23
	v_add_u32_e32 v21, 0xdc000, v112
	v_mov_b32_e32 v20, v131
	global_store_dwordx4 v21, v[16:19], s[18:19]
	v_pk_mul_f32 v[10:11], v[10:11], v[14:15]
	v_pk_mul_f32 v[22:23], v[12:13], v[20:21] op_sel_hi:[1,0]
	v_pk_mul_f32 v[16:17], v[14:15], v[20:21] op_sel_hi:[1,0]
	v_pk_mul_f32 v[8:9], v[8:9], v[12:13]
	v_exp_f32_e32 v16, v16
	v_exp_f32_e32 v14, v17
	v_exp_f32_e32 v22, v22
	v_exp_f32_e32 v19, v23
	v_fma_f32 v12, v16, v129, v129
	v_fma_f32 v13, v14, v129, v129
	v_rcp_f32_e32 v12, v12
	v_rcp_f32_e32 v13, v13
	v_pk_mul_f32 v[14:15], v[4:5], v[20:21] op_sel_hi:[1,0]
	v_fma_f32 v18, v22, v129, v129
	v_exp_f32_e32 v14, v14
	v_pk_mul_f32 v[10:11], v[10:11], v[12:13]
	v_pk_mul_f32 v[12:13], v[6:7], v[20:21] op_sel_hi:[1,0]
	v_exp_f32_e32 v15, v15
	v_exp_f32_e32 v12, v12
	v_exp_f32_e32 v13, v13
	v_fma_f32 v19, v19, v129, v129
	v_fma_f32 v14, v14, v129, v129
	v_fma_f32 v15, v15, v129, v129
	v_fma_f32 v12, v12, v129, v129
	v_fmac_f32_e32 v129, v13, v129
	v_rcp_f32_e32 v18, v18
	v_rcp_f32_e32 v19, v19
	v_rcp_f32_e32 v14, v14
	v_rcp_f32_e32 v15, v15
	v_rcp_f32_e32 v12, v12
	v_rcp_f32_e32 v13, v129
	v_pk_mul_f32 v[2:3], v[2:3], v[6:7]
	v_pk_mul_f32 v[0:1], v[0:1], v[4:5]
	v_pk_mul_f32 v[8:9], v[8:9], v[18:19]
	v_pk_mul_f32 v[4:5], v[0:1], v[14:15]
	v_pk_mul_f32 v[6:7], v[2:3], v[12:13]
	v_cvt_pk_bf16_f32 v0, v8, v9
	v_cvt_pk_bf16_f32 v1, v10, v11
	v_cvt_pk_bf16_f32 v2, v4, v5
	v_cvt_pk_bf16_f32 v3, v6, v7
	v_add_u32_e32 v4, 0xf2000, v112
	s_and_b64 vcc, exec, s[42:43]
	s_mov_b64 s[10:11], -1
	global_store_dwordx4 v4, v[0:3], s[18:19]
	s_cbranch_vccnz .LBB0_385
	s_andn2_b64 vcc, exec, s[12:13]
	s_cbranch_vccnz .LBB0_384
	s_mov_b32 s100, 1
	s_branch .LBB0_384

.LBB0_1150:
	ds_read2_b32 v[156:157], v153 offset1:16
	s_waitcnt lgkmcnt(0)
	v_add_u32_e32 v128, 0x1000, v153
	ds_read2_b32 v[158:159], v128 offset1:16
	ds_read2_b32 v[148:149], v153 offset0:32 offset1:48
	ds_read2_b32 v[146:147], v128 offset0:32 offset1:48
	ds_read2_b32 v[144:145], v153 offset0:64 offset1:80
	ds_read2_b32 v[142:143], v128 offset0:64 offset1:80
	ds_read2_b32 v[130:131], v153 offset0:96 offset1:112
	ds_read2_b32 v[128:129], v128 offset0:96 offset1:112
	v_pk_mul_f32 v[114:115], v[114:115], v[118:119]
	v_pk_mul_f32 v[112:113], v[112:113], v[116:117]
	s_waitcnt vmcnt(0)
	v_pk_mul_f32 v[160:161], v[120:121], v[156:157] op_sel_hi:[1,0]
	v_pk_mul_f32 v[162:163], v[122:123], v[156:157] op_sel_hi:[1,0]
	v_exp_f32_e32 v161, v161
	v_pk_mul_f32 v[122:123], v[126:127], v[122:123]
	v_exp_f32_e32 v126, v163
	v_pk_mul_f32 v[120:121], v[124:125], v[120:121]
	s_waitcnt lgkmcnt(6)
	v_fma_f32 v161, v161, v158, v158
	v_rcp_f32_e32 v165, v161
	v_exp_f32_e32 v161, v162
	v_fma_f32 v125, v126, v158, v158
	v_rcp_f32_e32 v125, v125
	v_pk_mul_f32 v[126:127], v[116:117], v[156:157] op_sel_hi:[1,0]
	v_fma_f32 v124, v161, v158, v158
	v_rcp_f32_e32 v124, v124
	v_exp_f32_e32 v164, v160
	v_exp_f32_e32 v126, v126
	v_exp_f32_e32 v127, v127
	v_pk_mul_f32 v[122:123], v[122:123], v[124:125]
	v_pk_mul_f32 v[124:125], v[118:119], v[156:157] op_sel_hi:[1,0]
	v_fma_f32 v164, v164, v158, v158
	v_exp_f32_e32 v124, v124
	v_exp_f32_e32 v125, v125
	v_fma_f32 v126, v126, v158, v158
	v_fma_f32 v127, v127, v158, v158
	v_fma_f32 v124, v124, v158, v158
	v_fma_f32 v125, v125, v158, v158
	v_rcp_f32_e32 v124, v124
	v_rcp_f32_e32 v125, v125
	v_rcp_f32_e32 v164, v164
	v_rcp_f32_e32 v126, v126
	v_rcp_f32_e32 v127, v127
	v_pk_mul_f32 v[118:119], v[114:115], v[124:125]
	v_or_b32_e32 v166, s10, v150
	v_lshl_or_b32 v160, s60, 8, v154
	v_pk_mul_f32 v[120:121], v[120:121], v[164:165]
	v_pk_mul_f32 v[112:113], v[112:113], v[126:127]
	v_cvt_pk_bf16_f32 v117, v118, v119
	s_movk_i32 s10, 0x1600
	v_mov_b32_e32 v118, v157
	v_cvt_pk_bf16_f32 v114, v120, v121
	v_cvt_pk_bf16_f32 v116, v112, v113
	v_mad_u64_u32 v[112:113], s[10:11], v166, s10, v[160:161]
	v_pk_mul_f32 v[120:121], v[108:109], v[118:119] op_sel_hi:[1,0]
	v_cvt_pk_bf16_f32 v115, v122, v123
	v_exp_f32_e32 v113, v120
	global_store_dwordx4 v112, v[114:117], s[18:19]
	v_pk_mul_f32 v[106:107], v[106:107], v[110:111]
	v_pk_mul_f32 v[104:105], v[104:105], v[108:109]
	v_exp_f32_e32 v117, v121
	v_fma_f32 v113, v113, v159, v159
	v_pk_mul_f32 v[114:115], v[110:111], v[118:119] op_sel_hi:[1,0]
	v_rcp_f32_e32 v116, v113
	v_fma_f32 v113, v117, v159, v159
	v_rcp_f32_e32 v117, v113
	v_exp_f32_e32 v113, v114
	v_exp_f32_e32 v110, v115
	v_pk_mul_f32 v[98:99], v[98:99], v[102:103]
	v_pk_mul_f32 v[96:97], v[96:97], v[100:101]
	v_fma_f32 v108, v113, v159, v159
	v_fma_f32 v109, v110, v159, v159
	v_rcp_f32_e32 v108, v108
	v_rcp_f32_e32 v109, v109
	v_pk_mul_f32 v[110:111], v[100:101], v[118:119] op_sel_hi:[1,0]
	v_pk_mul_f32 v[104:105], v[104:105], v[116:117]
	v_exp_f32_e32 v110, v110
	v_pk_mul_f32 v[106:107], v[106:107], v[108:109]
	v_pk_mul_f32 v[108:109], v[102:103], v[118:119] op_sel_hi:[1,0]
	v_exp_f32_e32 v111, v111
	v_exp_f32_e32 v108, v108
	v_exp_f32_e32 v109, v109
	v_fma_f32 v110, v110, v159, v159
	v_fma_f32 v111, v111, v159, v159
	v_fma_f32 v108, v108, v159, v159
	v_fmac_f32_e32 v159, v109, v159
	v_rcp_f32_e32 v110, v110
	v_rcp_f32_e32 v111, v111
	v_rcp_f32_e32 v108, v108
	v_rcp_f32_e32 v109, v159
	v_pk_mul_f32 v[90:91], v[90:91], v[94:95]
	v_pk_mul_f32 v[100:101], v[96:97], v[110:111]
	v_cvt_pk_bf16_f32 v96, v104, v105
	v_pk_mul_f32 v[102:103], v[98:99], v[108:109]
	v_cvt_pk_bf16_f32 v97, v106, v107
	v_cvt_pk_bf16_f32 v98, v100, v101
	v_cvt_pk_bf16_f32 v99, v102, v103
	v_add_u32_e32 v102, 0x16000, v112
	global_store_dwordx4 v102, v[96:99], s[18:19]
	s_waitcnt lgkmcnt(5)
	v_pk_mul_f32 v[100:101], v[92:93], v[148:149] op_sel_hi:[1,0]
	v_pk_mul_f32 v[88:89], v[88:89], v[92:93]
	v_pk_mul_f32 v[96:97], v[94:95], v[148:149] op_sel_hi:[1,0]
	v_exp_f32_e32 v100, v100
	v_exp_f32_e32 v96, v96
	v_exp_f32_e32 v94, v97
	v_exp_f32_e32 v99, v101
	s_waitcnt lgkmcnt(4)
	v_fma_f32 v98, v100, v146, v146
	v_fma_f32 v92, v96, v146, v146
	v_fma_f32 v93, v94, v146, v146
	v_rcp_f32_e32 v92, v92
	v_rcp_f32_e32 v93, v93
	v_pk_mul_f32 v[94:95], v[84:85], v[148:149] op_sel_hi:[1,0]
	v_fma_f32 v99, v99, v146, v146
	v_exp_f32_e32 v94, v94
	v_pk_mul_f32 v[90:91], v[90:91], v[92:93]
	v_pk_mul_f32 v[92:93], v[86:87], v[148:149] op_sel_hi:[1,0]
	v_exp_f32_e32 v95, v95
	v_exp_f32_e32 v92, v92
	v_exp_f32_e32 v93, v93
	v_fma_f32 v94, v94, v146, v146
	v_fma_f32 v95, v95, v146, v146
	v_fma_f32 v92, v92, v146, v146
	v_fma_f32 v93, v93, v146, v146
	v_rcp_f32_e32 v98, v98
	v_rcp_f32_e32 v99, v99
	v_rcp_f32_e32 v94, v94
	v_rcp_f32_e32 v95, v95
	v_rcp_f32_e32 v92, v92
	v_rcp_f32_e32 v93, v93
	v_pk_mul_f32 v[82:83], v[82:83], v[86:87]
	v_pk_mul_f32 v[80:81], v[80:81], v[84:85]
	v_pk_mul_f32 v[88:89], v[88:89], v[98:99]
	v_pk_mul_f32 v[84:85], v[80:81], v[94:95]
	v_pk_mul_f32 v[86:87], v[82:83], v[92:93]
	v_cvt_pk_bf16_f32 v80, v88, v89
	v_cvt_pk_bf16_f32 v81, v90, v91
	v_cvt_pk_bf16_f32 v82, v84, v85
	v_cvt_pk_bf16_f32 v83, v86, v87
	v_add_u32_e32 v85, 0x2c000, v112
	v_mov_b32_e32 v84, v149
	global_store_dwordx4 v85, v[80:83], s[18:19]
	v_pk_mul_f32 v[74:75], v[74:75], v[78:79]
	v_pk_mul_f32 v[86:87], v[76:77], v[84:85] op_sel_hi:[1,0]
	v_pk_mul_f32 v[80:81], v[78:79], v[84:85] op_sel_hi:[1,0]
	v_pk_mul_f32 v[72:73], v[72:73], v[76:77]
	v_exp_f32_e32 v80, v80
	v_exp_f32_e32 v78, v81
	v_exp_f32_e32 v86, v86
	v_exp_f32_e32 v83, v87
	v_fma_f32 v76, v80, v147, v147
	v_fma_f32 v77, v78, v147, v147
	v_rcp_f32_e32 v76, v76
	v_rcp_f32_e32 v77, v77
	v_pk_mul_f32 v[78:79], v[68:69], v[84:85] op_sel_hi:[1,0]
	v_fma_f32 v82, v86, v147, v147
	v_exp_f32_e32 v78, v78
	v_pk_mul_f32 v[74:75], v[74:75], v[76:77]
	v_pk_mul_f32 v[76:77], v[70:71], v[84:85] op_sel_hi:[1,0]
	v_exp_f32_e32 v79, v79
	v_exp_f32_e32 v76, v76
	v_exp_f32_e32 v77, v77
	v_fma_f32 v83, v83, v147, v147
	v_fma_f32 v78, v78, v147, v147
	v_fma_f32 v79, v79, v147, v147
	v_fma_f32 v76, v76, v147, v147
	v_fmac_f32_e32 v147, v77, v147
	v_rcp_f32_e32 v82, v82
	v_rcp_f32_e32 v83, v83
	v_rcp_f32_e32 v78, v78
	v_rcp_f32_e32 v79, v79
	v_rcp_f32_e32 v76, v76
	v_rcp_f32_e32 v77, v147
	v_pk_mul_f32 v[66:67], v[66:67], v[70:71]
	v_pk_mul_f32 v[64:65], v[64:65], v[68:69]
	v_pk_mul_f32 v[72:73], v[72:73], v[82:83]
	v_pk_mul_f32 v[68:69], v[64:65], v[78:79]
	v_pk_mul_f32 v[70:71], v[66:67], v[76:77]
	v_cvt_pk_bf16_f32 v64, v72, v73
	v_cvt_pk_bf16_f32 v65, v74, v75
	v_cvt_pk_bf16_f32 v66, v68, v69
	v_cvt_pk_bf16_f32 v67, v70, v71
	v_add_u32_e32 v70, 0x42000, v112
	global_store_dwordx4 v70, v[64:67], s[18:19]
	v_pk_mul_f32 v[58:59], v[58:59], v[62:63]
	s_waitcnt lgkmcnt(3)
	v_pk_mul_f32 v[68:69], v[60:61], v[144:145] op_sel_hi:[1,0]
	v_pk_mul_f32 v[64:65], v[62:63], v[144:145] op_sel_hi:[1,0]
	v_pk_mul_f32 v[56:57], v[56:57], v[60:61]
	v_exp_f32_e32 v64, v64
	v_exp_f32_e32 v62, v65
	v_exp_f32_e32 v68, v68
	v_exp_f32_e32 v67, v69
	s_waitcnt lgkmcnt(2)
	v_fma_f32 v60, v64, v142, v142
	v_fma_f32 v61, v62, v142, v142
	v_rcp_f32_e32 v60, v60
	v_rcp_f32_e32 v61, v61
	v_pk_mul_f32 v[62:63], v[52:53], v[144:145] op_sel_hi:[1,0]
	v_fma_f32 v66, v68, v142, v142
	v_exp_f32_e32 v62, v62
	v_pk_mul_f32 v[58:59], v[58:59], v[60:61]
	v_pk_mul_f32 v[60:61], v[54:55], v[144:145] op_sel_hi:[1,0]
	v_exp_f32_e32 v63, v63
	v_exp_f32_e32 v60, v60
	v_exp_f32_e32 v61, v61
	v_fma_f32 v67, v67, v142, v142
	v_fma_f32 v62, v62, v142, v142
	v_fma_f32 v63, v63, v142, v142
	v_fma_f32 v60, v60, v142, v142
	v_fma_f32 v61, v61, v142, v142
	v_rcp_f32_e32 v66, v66
	v_rcp_f32_e32 v67, v67
	v_rcp_f32_e32 v62, v62
	v_rcp_f32_e32 v63, v63
	v_rcp_f32_e32 v60, v60
	v_rcp_f32_e32 v61, v61
	v_pk_mul_f32 v[50:51], v[50:51], v[54:55]
	v_pk_mul_f32 v[48:49], v[48:49], v[52:53]
	v_pk_mul_f32 v[56:57], v[56:57], v[66:67]
	v_pk_mul_f32 v[52:53], v[48:49], v[62:63]
	v_pk_mul_f32 v[54:55], v[50:51], v[60:61]
	v_cvt_pk_bf16_f32 v48, v56, v57
	v_cvt_pk_bf16_f32 v49, v58, v59
	v_cvt_pk_bf16_f32 v50, v52, v53
	v_cvt_pk_bf16_f32 v51, v54, v55
	v_add_u32_e32 v53, 0xb0000, v112
	v_mov_b32_e32 v52, v145
	global_store_dwordx4 v53, v[48:51], s[18:19]
	v_pk_mul_f32 v[42:43], v[42:43], v[46:47]
	v_pk_mul_f32 v[54:55], v[44:45], v[52:53] op_sel_hi:[1,0]
	v_pk_mul_f32 v[48:49], v[46:47], v[52:53] op_sel_hi:[1,0]
	v_pk_mul_f32 v[40:41], v[40:41], v[44:45]
	v_exp_f32_e32 v48, v48
	v_exp_f32_e32 v46, v49
	v_exp_f32_e32 v54, v54
	v_exp_f32_e32 v51, v55
	v_fma_f32 v44, v48, v143, v143
	v_fma_f32 v45, v46, v143, v143
	v_rcp_f32_e32 v44, v44
	v_rcp_f32_e32 v45, v45
	v_pk_mul_f32 v[46:47], v[36:37], v[52:53] op_sel_hi:[1,0]
	v_fma_f32 v50, v54, v143, v143
	v_exp_f32_e32 v46, v46
	v_pk_mul_f32 v[42:43], v[42:43], v[44:45]
	v_pk_mul_f32 v[44:45], v[38:39], v[52:53] op_sel_hi:[1,0]
	v_exp_f32_e32 v47, v47
	v_exp_f32_e32 v44, v44
	v_exp_f32_e32 v45, v45
	v_fma_f32 v51, v51, v143, v143
	v_fma_f32 v46, v46, v143, v143
	v_fma_f32 v47, v47, v143, v143
	v_fma_f32 v44, v44, v143, v143
	v_fmac_f32_e32 v143, v45, v143
	v_rcp_f32_e32 v50, v50
	v_rcp_f32_e32 v51, v51
	v_rcp_f32_e32 v46, v46
	v_rcp_f32_e32 v47, v47
	v_rcp_f32_e32 v44, v44
	v_rcp_f32_e32 v45, v143
	v_pk_mul_f32 v[34:35], v[34:35], v[38:39]
	v_pk_mul_f32 v[32:33], v[32:33], v[36:37]
	v_pk_mul_f32 v[40:41], v[40:41], v[50:51]
	v_pk_mul_f32 v[36:37], v[32:33], v[46:47]
	v_pk_mul_f32 v[38:39], v[34:35], v[44:45]
	v_cvt_pk_bf16_f32 v32, v40, v41
	v_cvt_pk_bf16_f32 v33, v42, v43
	v_cvt_pk_bf16_f32 v34, v36, v37
	v_cvt_pk_bf16_f32 v35, v38, v39
	v_add_u32_e32 v38, 0xc6000, v112
	global_store_dwordx4 v38, v[32:35], s[18:19]
	v_pk_mul_f32 v[26:27], v[26:27], v[30:31]
	s_waitcnt lgkmcnt(1)
	v_pk_mul_f32 v[36:37], v[28:29], v[130:131] op_sel_hi:[1,0]
	v_pk_mul_f32 v[32:33], v[30:31], v[130:131] op_sel_hi:[1,0]
	v_pk_mul_f32 v[24:25], v[24:25], v[28:29]
	v_exp_f32_e32 v32, v32
	v_exp_f32_e32 v30, v33
	v_exp_f32_e32 v36, v36
	v_exp_f32_e32 v35, v37
	s_waitcnt lgkmcnt(0)
	v_fma_f32 v28, v32, v128, v128
	v_fma_f32 v29, v30, v128, v128
	v_rcp_f32_e32 v28, v28
	v_rcp_f32_e32 v29, v29
	v_pk_mul_f32 v[30:31], v[20:21], v[130:131] op_sel_hi:[1,0]
	v_fma_f32 v34, v36, v128, v128
	v_exp_f32_e32 v30, v30
	v_pk_mul_f32 v[26:27], v[26:27], v[28:29]
	v_pk_mul_f32 v[28:29], v[22:23], v[130:131] op_sel_hi:[1,0]
	v_exp_f32_e32 v31, v31
	v_exp_f32_e32 v28, v28
	v_exp_f32_e32 v29, v29
	v_fma_f32 v35, v35, v128, v128
	v_fma_f32 v30, v30, v128, v128
	v_fma_f32 v31, v31, v128, v128
	v_fma_f32 v28, v28, v128, v128
	v_fma_f32 v29, v29, v128, v128
	v_rcp_f32_e32 v34, v34
	v_rcp_f32_e32 v35, v35
	v_rcp_f32_e32 v30, v30
	v_rcp_f32_e32 v31, v31
	v_rcp_f32_e32 v28, v28
	v_rcp_f32_e32 v29, v29
	v_pk_mul_f32 v[18:19], v[18:19], v[22:23]
	v_pk_mul_f32 v[16:17], v[16:17], v[20:21]
	v_pk_mul_f32 v[24:25], v[24:25], v[34:35]
	v_pk_mul_f32 v[20:21], v[16:17], v[30:31]
	v_pk_mul_f32 v[22:23], v[18:19], v[28:29]
	v_cvt_pk_bf16_f32 v16, v24, v25
	v_cvt_pk_bf16_f32 v17, v26, v27
	v_cvt_pk_bf16_f32 v18, v20, v21
	v_cvt_pk_bf16_f32 v19, v22, v23
	v_add_u32_e32 v21, 0xdc000, v112
	v_mov_b32_e32 v20, v131
	global_store_dwordx4 v21, v[16:19], s[18:19]
	v_pk_mul_f32 v[10:11], v[10:11], v[14:15]
	v_pk_mul_f32 v[22:23], v[12:13], v[20:21] op_sel_hi:[1,0]
	v_pk_mul_f32 v[16:17], v[14:15], v[20:21] op_sel_hi:[1,0]
	v_pk_mul_f32 v[8:9], v[8:9], v[12:13]
	v_exp_f32_e32 v16, v16
	v_exp_f32_e32 v14, v17
	v_exp_f32_e32 v22, v22
	v_exp_f32_e32 v19, v23
	v_fma_f32 v12, v16, v129, v129
	v_fma_f32 v13, v14, v129, v129
	v_rcp_f32_e32 v12, v12
	v_rcp_f32_e32 v13, v13
	v_pk_mul_f32 v[14:15], v[4:5], v[20:21] op_sel_hi:[1,0]
	v_fma_f32 v18, v22, v129, v129
	v_exp_f32_e32 v14, v14
	v_pk_mul_f32 v[10:11], v[10:11], v[12:13]
	v_pk_mul_f32 v[12:13], v[6:7], v[20:21] op_sel_hi:[1,0]
	v_exp_f32_e32 v15, v15
	v_exp_f32_e32 v12, v12
	v_exp_f32_e32 v13, v13
	v_fma_f32 v19, v19, v129, v129
	v_fma_f32 v14, v14, v129, v129
	v_fma_f32 v15, v15, v129, v129
	v_fma_f32 v12, v12, v129, v129
	v_fmac_f32_e32 v129, v13, v129
	v_rcp_f32_e32 v18, v18
	v_rcp_f32_e32 v19, v19
	v_rcp_f32_e32 v14, v14
	v_rcp_f32_e32 v15, v15
	v_rcp_f32_e32 v12, v12
	v_rcp_f32_e32 v13, v129
	v_pk_mul_f32 v[2:3], v[2:3], v[6:7]
	v_pk_mul_f32 v[0:1], v[0:1], v[4:5]
	v_pk_mul_f32 v[8:9], v[8:9], v[18:19]
	v_pk_mul_f32 v[4:5], v[0:1], v[14:15]
	v_pk_mul_f32 v[6:7], v[2:3], v[12:13]
	v_cvt_pk_bf16_f32 v0, v8, v9
	v_cvt_pk_bf16_f32 v1, v10, v11
	v_cvt_pk_bf16_f32 v2, v4, v5
	v_cvt_pk_bf16_f32 v3, v6, v7
	v_add_u32_e32 v4, 0xf2000, v112
	s_and_b64 vcc, exec, s[42:43]
	s_mov_b64 s[10:11], -1
	global_store_dwordx4 v4, v[0:3], s[18:19]
	s_cbranch_vccnz .LBB0_1133
	s_andn2_b64 vcc, exec, s[14:15]
	s_cbranch_vccnz .LBB0_1132
	s_mov_b32 s100, 1
	s_branch .LBB0_1132
